# P0 weight-conversion f32 loads non-temporal (read once)
# speedup vs baseline: 1.0089x; 1.0089x over previous
; __device__ __forceinline__ void p0_convert(const Args& a, LAS float* scr, int gw, int NGW, int lane) {
;     ...
;         const int ktiles = K >> 6, n0 = (r / ktiles) * 64, k0 = (r % ktiles) * 64, n = n0 + lane;
;         const float* sp; int srcN;
;         if (kind == 0) { sp = a.in[I_WIN] + (n < 4608 ? n : n + 16); srcN = DIN; }
;         else if (kind == 1) { sp = a.in[I_WPA] + n; srcN = 1024; }
;         else if (kind == 2) { sp = a.in[I_WPB] + n; srcN = 1024; }
;         else if (kind == 3) { sp = a.in[I_WOUT] + n; srcN = 1024; }
;         else if (kind == 4) { const int pn = n >> 8, rr = n & 255; sp = ((rr < 128) ? a.in[I_WG] : a.in[I_WU]) + 128 * pn + (rr & 127); srcN = DFF; }
;         else { sp = a.in[I_WD] + n; srcN = 1024; }
;         sp += (size_t)k0 * srcN;
;         float tmp[64];
; #pragma unroll
;         for (int i = 0; i < 64; ++i) tmp[i] = sp[(size_t)i * srcN];
.LBB0_125:
	s_mul_i32 s76, s76, s3
	s_sub_i32 s3, s74, s76
	s_lshl_b32 s3, s3, 6
	s_ashr_i32 s10, s3, 31
	s_mul_i32 s8, s30, s10
	s_mul_hi_u32 s9, s30, s3
	s_add_i32 s8, s9, s8
	s_mul_i32 s9, s31, s3
	s_add_i32 s9, s8, s9
	s_mul_i32 s8, s30, s3
	v_lshl_add_u64 v[4:5], s[8:9], 2, v[6:7]
	s_lshl_b64 s[8:9], s[30:31], 2
	v_lshl_add_u64 v[6:7], v[4:5], 0, s[8:9]
	v_lshl_add_u64 v[8:9], v[6:7], 0, s[8:9]
	v_lshl_add_u64 v[10:11], v[8:9], 0, s[8:9]
	v_lshl_add_u64 v[12:13], v[10:11], 0, s[8:9]
	v_lshl_add_u64 v[14:15], v[12:13], 0, s[8:9]
	v_lshl_add_u64 v[16:17], v[14:15], 0, s[8:9]
	v_lshl_add_u64 v[18:19], v[16:17], 0, s[8:9]
	global_load_dword v0, v[4:5], off nt
	global_load_dword v30, v[6:7], off nt
	s_nop 0
	global_load_dword v8, v[8:9], off nt
	s_nop 0
	global_load_dword v9, v[10:11], off nt
	s_nop 0
	global_load_dword v10, v[12:13], off nt
	global_load_dword v11, v[14:15], off nt
	s_nop 0
	global_load_dword v12, v[16:17], off nt
	global_load_dword v13, v[18:19], off nt
	v_lshl_add_u64 v[4:5], v[18:19], 0, s[8:9]
	v_lshl_add_u64 v[6:7], v[4:5], 0, s[8:9]
	global_load_dword v14, v[4:5], off nt
	global_load_dword v15, v[6:7], off nt
	v_lshl_add_u64 v[4:5], v[6:7], 0, s[8:9]
	global_load_dword v6, v[4:5], off nt
	v_lshl_add_u64 v[4:5], v[4:5], 0, s[8:9]
	global_load_dword v7, v[4:5], off nt
	v_lshl_add_u64 v[4:5], v[4:5], 0, s[8:9]
	global_load_dword v16, v[4:5], off nt
	v_lshl_add_u64 v[4:5], v[4:5], 0, s[8:9]
	global_load_dword v17, v[4:5], off nt
	v_lshl_add_u64 v[4:5], v[4:5], 0, s[8:9]
	global_load_dword v18, v[4:5], off nt
	v_lshl_add_u64 v[4:5], v[4:5], 0, s[8:9]
	global_load_dword v19, v[4:5], off nt
	v_lshl_add_u64 v[4:5], v[4:5], 0, s[8:9]
	global_load_dword v31, v[4:5], off nt
	v_lshl_add_u64 v[4:5], v[4:5], 0, s[8:9]
	global_load_dword v32, v[4:5], off nt
	v_lshl_add_u64 v[4:5], v[4:5], 0, s[8:9]
	global_load_dword v33, v[4:5], off nt
	v_lshl_add_u64 v[4:5], v[4:5], 0, s[8:9]
	global_load_dword v34, v[4:5], off nt
	v_lshl_add_u64 v[4:5], v[4:5], 0, s[8:9]
	global_load_dword v35, v[4:5], off nt
	v_lshl_add_u64 v[4:5], v[4:5], 0, s[8:9]
	global_load_dword v36, v[4:5], off nt
	v_lshl_add_u64 v[4:5], v[4:5], 0, s[8:9]
	global_load_dword v37, v[4:5], off nt
	v_lshl_add_u64 v[4:5], v[4:5], 0, s[8:9]
	global_load_dword v38, v[4:5], off nt
	v_lshl_add_u64 v[4:5], v[4:5], 0, s[8:9]
	global_load_dword v39, v[4:5], off nt
	v_lshl_add_u64 v[4:5], v[4:5], 0, s[8:9]
	global_load_dword v40, v[4:5], off nt
	v_lshl_add_u64 v[4:5], v[4:5], 0, s[8:9]
	global_load_dword v41, v[4:5], off nt
	v_lshl_add_u64 v[4:5], v[4:5], 0, s[8:9]
	global_load_dword v42, v[4:5], off nt
	v_lshl_add_u64 v[4:5], v[4:5], 0, s[8:9]
	global_load_dword v43, v[4:5], off nt
	v_lshl_add_u64 v[4:5], v[4:5], 0, s[8:9]
	global_load_dword v44, v[4:5], off nt
	v_lshl_add_u64 v[4:5], v[4:5], 0, s[8:9]
	global_load_dword v45, v[4:5], off nt
	v_lshl_add_u64 v[4:5], v[4:5], 0, s[8:9]
	global_load_dword v46, v[4:5], off nt
	v_lshl_add_u64 v[4:5], v[4:5], 0, s[8:9]
	global_load_dword v47, v[4:5], off nt
	v_lshl_add_u64 v[4:5], v[4:5], 0, s[8:9]
	global_load_dword v48, v[4:5], off nt
	v_lshl_add_u64 v[4:5], v[4:5], 0, s[8:9]
	global_load_dword v49, v[4:5], off nt
	v_lshl_add_u64 v[4:5], v[4:5], 0, s[8:9]
	global_load_dword v50, v[4:5], off nt
	v_lshl_add_u64 v[4:5], v[4:5], 0, s[8:9]
	global_load_dword v51, v[4:5], off nt
	v_lshl_add_u64 v[4:5], v[4:5], 0, s[8:9]
	global_load_dword v52, v[4:5], off nt
	v_lshl_add_u64 v[4:5], v[4:5], 0, s[8:9]
	global_load_dword v53, v[4:5], off nt
	v_lshl_add_u64 v[4:5], v[4:5], 0, s[8:9]
	global_load_dword v54, v[4:5], off nt
	v_lshl_add_u64 v[4:5], v[4:5], 0, s[8:9]
	global_load_dword v55, v[4:5], off nt
	v_lshl_add_u64 v[4:5], v[4:5], 0, s[8:9]
	global_load_dword v56, v[4:5], off nt
	v_lshl_add_u64 v[4:5], v[4:5], 0, s[8:9]
	global_load_dword v57, v[4:5], off nt
	v_lshl_add_u64 v[4:5], v[4:5], 0, s[8:9]
	global_load_dword v58, v[4:5], off nt
	v_lshl_add_u64 v[4:5], v[4:5], 0, s[8:9]
	global_load_dword v59, v[4:5], off nt
	v_lshl_add_u64 v[4:5], v[4:5], 0, s[8:9]
	global_load_dword v60, v[4:5], off nt
	v_lshl_add_u64 v[4:5], v[4:5], 0, s[8:9]
	global_load_dword v61, v[4:5], off nt
	v_lshl_add_u64 v[4:5], v[4:5], 0, s[8:9]
	global_load_dword v62, v[4:5], off nt
	v_lshl_add_u64 v[4:5], v[4:5], 0, s[8:9]
	global_load_dword v63, v[4:5], off nt
	v_lshl_add_u64 v[4:5], v[4:5], 0, s[8:9]
	global_load_dword v64, v[4:5], off nt
	v_lshl_add_u64 v[4:5], v[4:5], 0, s[8:9]
	global_load_dword v65, v[4:5], off nt
	v_lshl_add_u64 v[4:5], v[4:5], 0, s[8:9]
	global_load_dword v66, v[4:5], off nt
	v_lshl_add_u64 v[4:5], v[4:5], 0, s[8:9]
	global_load_dword v67, v[4:5], off nt
	v_lshl_add_u64 v[4:5], v[4:5], 0, s[8:9]
	global_load_dword v68, v[4:5], off nt
	v_lshl_add_u64 v[4:5], v[4:5], 0, s[8:9]
	global_load_dword v69, v[4:5], off nt
	v_lshl_add_u64 v[4:5], v[4:5], 0, s[8:9]
	global_load_dword v70, v[4:5], off nt
	v_lshl_add_u64 v[4:5], v[4:5], 0, s[8:9]
	global_load_dword v71, v[4:5], off nt
	v_lshl_add_u64 v[4:5], v[4:5], 0, s[8:9]
	global_load_dword v72, v[4:5], off nt
	v_lshl_add_u64 v[4:5], v[4:5], 0, s[8:9]
	global_load_dword v73, v[4:5], off nt
	v_lshl_add_u64 v[4:5], v[4:5], 0, s[8:9]
	global_load_dword v74, v[4:5], off nt
	v_lshl_add_u64 v[4:5], v[4:5], 0, s[8:9]
	global_load_dword v75, v[4:5], off nt
	v_lshl_add_u64 v[4:5], v[4:5], 0, s[8:9]
	global_load_dword v76, v[4:5], off nt
	v_lshl_add_u64 v[4:5], v[4:5], 0, s[8:9]
	global_load_dword v77, v[4:5], off nt
	v_lshl_add_u64 v[4:5], v[4:5], 0, s[8:9]
	global_load_dword v4, v[4:5], off nt
	s_ashr_i32 s8, s75, 31
	s_mul_hi_u32 s9, s75, s0
	s_mul_i32 s8, s8, s0
	s_add_i32 s9, s9, s8
	s_mul_i32 s75, s75, s0
	s_add_u32 s8, s75, s3
	s_addc_u32 s9, s9, s10
	s_lshr_b32 s3, s0, 1
	s_waitcnt vmcnt(62)
; __device__ __forceinline__ unsigned cvt_pk_bf16(float lo, float hi) { f32x2 v = {lo, hi}; bf16x2_t b = __builtin_convertvector(v, bf16x2_t); return __builtin_bit_cast(unsigned, b); }
; __device__ __forceinline__ void wave_lds_sync() { asm volatile("s_waitcnt lgkmcnt(0)" ::: "memory"); __builtin_amdgcn_wave_barrier(); }
; __device__ __forceinline__ void p0_convert(const Args& a, LAS float* scr, int gw, int NGW, int lane) {
;     ...
; #pragma unroll
;         for (int i = 0; i < 64; ++i) scr[lane * 65 + i] = tmp[i];
;         wave_lds_sync();
;         unsigned* dst = (unsigned*)(a.ws + dsto) + ((size_t)n0 * K + k0) / 2 + (lane & 31);
; #pragma unroll 8
;         for (int j = 0; j < 32; ++j) { const int row = 2 * j + (lane >> 5), kk = (lane & 31) * 2; dst[(size_t)row * (K / 2)] = cvt_pk_bf16(scr[row * 65 + kk], scr[row * 65 + kk + 1]); }
	ds_write2_b32 v29, v0, v30 offset1:1
	s_waitcnt vmcnt(60)
	ds_write2_b32 v29, v8, v9 offset0:2 offset1:3
	s_waitcnt vmcnt(58)
	ds_write2_b32 v29, v10, v11 offset0:4 offset1:5
	s_waitcnt vmcnt(56)
	ds_write2_b32 v29, v12, v13 offset0:6 offset1:7
	s_waitcnt vmcnt(54)
	ds_write2_b32 v29, v14, v15 offset0:8 offset1:9
	s_waitcnt vmcnt(52)
	ds_write2_b32 v29, v6, v7 offset0:10 offset1:11
	s_waitcnt vmcnt(50)
	ds_write2_b32 v29, v16, v17 offset0:12 offset1:13
	s_waitcnt vmcnt(48)
	ds_write2_b32 v29, v18, v19 offset0:14 offset1:15
	s_waitcnt vmcnt(46)
	ds_write2_b32 v29, v31, v32 offset0:16 offset1:17
	s_waitcnt vmcnt(44)
	ds_write2_b32 v29, v33, v34 offset0:18 offset1:19
	s_waitcnt vmcnt(42)
	ds_write2_b32 v29, v35, v36 offset0:20 offset1:21
	s_waitcnt vmcnt(40)
	ds_write2_b32 v29, v37, v38 offset0:22 offset1:23
	s_waitcnt vmcnt(38)
	ds_write2_b32 v29, v39, v40 offset0:24 offset1:25
	s_waitcnt vmcnt(36)
	ds_write2_b32 v29, v41, v42 offset0:26 offset1:27
	s_waitcnt vmcnt(34)
	ds_write2_b32 v29, v43, v44 offset0:28 offset1:29
	s_waitcnt vmcnt(32)
	ds_write2_b32 v29, v45, v46 offset0:30 offset1:31
	s_waitcnt vmcnt(30)
	ds_write2_b32 v29, v47, v48 offset0:32 offset1:33
	s_waitcnt vmcnt(28)
	ds_write2_b32 v29, v49, v50 offset0:34 offset1:35
	s_waitcnt vmcnt(26)
	ds_write2_b32 v29, v51, v52 offset0:36 offset1:37
	s_waitcnt vmcnt(24)
	ds_write2_b32 v29, v53, v54 offset0:38 offset1:39
	s_waitcnt vmcnt(22)
	ds_write2_b32 v29, v55, v56 offset0:40 offset1:41
	s_waitcnt vmcnt(20)
	ds_write2_b32 v29, v57, v58 offset0:42 offset1:43
	s_waitcnt vmcnt(18)
	ds_write2_b32 v29, v59, v60 offset0:44 offset1:45
	s_waitcnt vmcnt(16)
	ds_write2_b32 v29, v61, v62 offset0:46 offset1:47
	s_waitcnt vmcnt(14)
	ds_write2_b32 v29, v63, v64 offset0:48 offset1:49
	s_waitcnt vmcnt(12)
	ds_write2_b32 v29, v65, v66 offset0:50 offset1:51
	s_waitcnt vmcnt(10)
	ds_write2_b32 v29, v67, v68 offset0:52 offset1:53
	s_waitcnt vmcnt(8)
	ds_write2_b32 v29, v69, v70 offset0:54 offset1:55
	s_waitcnt vmcnt(6)
	ds_write2_b32 v29, v71, v72 offset0:56 offset1:57
	s_waitcnt vmcnt(4)
	ds_write2_b32 v29, v73, v74 offset0:58 offset1:59
	s_waitcnt vmcnt(2)
	ds_write2_b32 v29, v75, v76 offset0:60 offset1:61
	s_waitcnt vmcnt(0)
	ds_write2_b32 v29, v77, v4 offset0:62 offset1:63
	v_mul_lo_u32 v0, v21, s3
	v_lshl_add_u64 v[4:5], v[0:1], 2, s[6:7]
	v_mul_lo_u32 v0, v23, s3
	v_lshl_add_u64 v[6:7], v[0:1], 2, s[6:7]
	v_mul_lo_u32 v0, v24, s3
	v_lshl_add_u64 v[8:9], v[0:1], 2, s[6:7]
	v_mul_lo_u32 v0, v25, s3
	v_lshl_add_u64 v[10:11], v[0:1], 2, s[6:7]
	v_mul_lo_u32 v0, v26, s3
	v_lshl_add_u64 v[12:13], v[0:1], 2, s[6:7]
	v_mul_lo_u32 v0, v27, s3
	v_lshl_add_u64 v[14:15], v[0:1], 2, s[6:7]
	v_mul_lo_u32 v0, v28, s3
	s_waitcnt lgkmcnt(0)
	v_lshl_add_u64 v[16:17], v[0:1], 2, s[6:7]
	v_mul_lo_u32 v0, v20, s3
	v_lshl_add_u64 v[18:19], v[0:1], 2, s[6:7]
	s_lshl_b64 s[8:9], s[8:9], 1
	v_lshl_add_u64 v[4:5], v[2:3], 0, v[4:5]
	s_lshl_b64 s[10:11], s[0:1], 5
	v_lshl_add_u64 v[6:7], v[2:3], 0, v[6:7]
	v_lshl_add_u64 v[8:9], v[2:3], 0, v[8:9]
	v_lshl_add_u64 v[10:11], v[2:3], 0, v[10:11]
	v_lshl_add_u64 v[12:13], v[2:3], 0, v[12:13]
	v_lshl_add_u64 v[14:15], v[2:3], 0, v[14:15]
	v_lshl_add_u64 v[16:17], v[2:3], 0, v[16:17]
	v_lshl_add_u64 v[18:19], v[2:3], 0, v[18:19]
	s_mov_b32 s0, 0
